# stack: Kt-tail D term via cndmask + attention threshold computed by wave 2 at kernel start (parked in LDS) + XCD leader not waiting for its release atomics
# baseline (speedup 1.0000x reference)
.Lgs_arrived:
	s_or_b64 exec, exec, s[6:7]
	v_cmp_eq_u32_e64 s[26:27], 0, v208
	v_and_b32_e32 v210, 63, v208
	v_readfirstlane_b32 s98, v208
	s_cmp_eq_u32 s98, 128
	s_cbranch_scc0 .Lthr_skip
	s_load_dwordx2 s[6:7], s[0:1], 0x28
	s_load_dwordx2 s[8:9], s[0:1], 0x30
	v_lshlrev_b32_e32 v0, 2, v210
	s_waitcnt lgkmcnt(0)
	global_load_dword v1, v0, s[6:7]
	global_load_dword v2, v0, s[8:9]
	v_mbcnt_lo_u32_b32 v0, -1, 0
	v_mbcnt_hi_u32_b32 v0, -1, v0
	v_and_b32_e32 v3, 64, v0
	v_xor_b32_e32 v4, 1, v0
	v_add_u32_e32 v3, 64, v3
	v_cmp_lt_i32_e32 vcc, v4, v3
	v_xor_b32_e32 v5, 2, v0
	v_xor_b32_e32 v6, 4, v0
	v_cndmask_b32_e32 v4, v0, v4, vcc
	v_lshlrev_b32_e32 v4, 2, v4
	v_cmp_lt_i32_e32 vcc, v5, v3
	v_xor_b32_e32 v7, 8, v0
	v_xor_b32_e32 v8, 16, v0
	v_cndmask_b32_e32 v5, v0, v5, vcc
	v_lshlrev_b32_e32 v5, 2, v5
	v_cmp_lt_i32_e32 vcc, v6, v3
	v_xor_b32_e32 v9, 32, v0
	v_cndmask_b32_e32 v6, v0, v6, vcc
	v_lshlrev_b32_e32 v6, 2, v6
	v_cmp_lt_i32_e32 vcc, v7, v3
	s_waitcnt lgkmcnt(0)
	v_cndmask_b32_e32 v7, v0, v7, vcc
	v_lshlrev_b32_e32 v7, 2, v7
	v_cmp_lt_i32_e32 vcc, v8, v3
	s_waitcnt vmcnt(1)
	v_and_b32_e32 v10, 0x7fffffff, v1
	ds_bpermute_b32 v10, v4, v10
	s_waitcnt vmcnt(0)
	v_and_b32_e32 v11, 0x7fffffff, v2
	ds_bpermute_b32 v4, v4, v11
	v_max_f32_e64 v1, |v1|, |v1|
	v_max_f32_e64 v2, |v2|, |v2|
	s_waitcnt lgkmcnt(1)
	v_max_f32_e32 v10, v10, v10
	v_max_f32_e32 v1, v1, v10
	s_waitcnt lgkmcnt(0)
	v_max_f32_e32 v4, v4, v4
	v_max_f32_e32 v2, v2, v4
	ds_bpermute_b32 v4, v5, v1
	ds_bpermute_b32 v5, v5, v2
	s_waitcnt lgkmcnt(1)
	v_max_f32_e32 v4, v4, v4
	v_max_f32_e32 v1, v1, v4
	s_waitcnt lgkmcnt(0)
	v_max_f32_e32 v4, v5, v5
	v_max_f32_e32 v2, v2, v4
	ds_bpermute_b32 v4, v6, v1
	ds_bpermute_b32 v5, v6, v2
	v_cndmask_b32_e32 v6, v0, v8, vcc
	v_cmp_lt_i32_e32 vcc, v9, v3
	v_lshlrev_b32_e32 v3, 2, v6
	s_waitcnt lgkmcnt(1)
	v_max_f32_e32 v4, v4, v4
	v_max_f32_e32 v1, v1, v4
	s_waitcnt lgkmcnt(0)
	v_max_f32_e32 v4, v5, v5
	v_max_f32_e32 v2, v2, v4
	ds_bpermute_b32 v4, v7, v1
	ds_bpermute_b32 v5, v7, v2
	v_cndmask_b32_e32 v0, v0, v9, vcc
	s_waitcnt lgkmcnt(1)
	v_max_f32_e32 v4, v4, v4
	v_max_f32_e32 v1, v1, v4
	s_waitcnt lgkmcnt(0)
	v_max_f32_e32 v4, v5, v5
	ds_bpermute_b32 v5, v3, v1
	v_max_f32_e32 v2, v2, v4
	ds_bpermute_b32 v3, v3, v2
	v_lshlrev_b32_e32 v4, 2, v0
	s_waitcnt lgkmcnt(1)
	v_max_f32_e32 v0, v5, v5
	v_max_f32_e32 v1, v1, v0
	s_waitcnt lgkmcnt(0)
	v_max_f32_e32 v0, v3, v3
	v_max_f32_e32 v0, v2, v0
	ds_bpermute_b32 v3, v4, v1
	ds_bpermute_b32 v2, v4, v0
	s_waitcnt lgkmcnt(0)
	v_max_f32_e32 v3, v3, v3
	v_max_f32_e32 v1, v1, v1
	v_max_f32_e32 v1, v1, v3
	v_max_f32_e32 v2, v2, v2
	v_max_f32_e32 v0, v0, v0
	v_max_f32_e32 v0, v0, v2
	v_mul_f32_e32 v1, 0x3f866666, v1
	v_mul_f32_e32 v0, v0, v1
	v_mul_f32_e32 v0, 0x42800000, v0
	v_mul_f32_e32 v0, 0x3e38aa3b, v0
	v_fmaak_f32 v5, 2.0, v0, 0x42200000
	v_cmp_eq_u32_e32 vcc, 128, v208
	s_and_saveexec_b64 s[6:7], vcc
	v_mov_b32_e32 v6, 0x22060
	ds_write_b32 v6, v5
	s_or_b64 exec, exec, s[6:7]
	s_waitcnt lgkmcnt(0)
.Lthr_skip:
.Lssa_447:
	s_mov_b64 s[6:7], s[0:1]
	s_load_dwordx2 s[6:7], s[6:7], 0xa8
	s_mov_b64 s[22:23], s[0:1]
	s_load_dwordx8 s[8:15], s[22:23], 0x48
	s_load_dwordx2 s[42:43], s[22:23], 0xa8
	v_lshrrev_b32_e32 v65, 5, v208
	s_waitcnt lgkmcnt(0)
	s_add_u32 s24, s6, 0x44800
	v_lshlrev_b32_e32 v3, 3, v208
	v_lshlrev_b32_e32 v0, 9, v65
	s_addc_u32 s25, s7, 0
	v_bfe_u32 v2, v208, 1, 4
	v_and_b32_e32 v4, 8, v3
	v_add_u32_e32 v67, 0, v0
	s_add_u32 s38, s42, 0x3200000
	v_add_u32_e32 v0, v67, v0
	v_lshlrev_b32_e32 v1, 6, v2
	v_lshlrev_b32_e32 v5, 2, v4
	s_addc_u32 s39, s43, 0
	v_add3_u32 v69, v0, v1, v5
	v_lshlrev_b32_e32 v0, 4, v208
	s_add_u32 s40, s42, 0x300000
	v_and_b32_e32 v8, 0x1f0, v0
	v_mov_b32_e32 v9, 0
	s_addc_u32 s41, s43, 0
	v_lshl_add_u64 v[0:1], s[42:43], 0, v[8:9]
	s_mov_b64 s[42:43], 0x3e00000
	v_lshl_add_u64 v[10:11], v[0:1], 0, s[42:43]
	v_cmp_eq_u32_e32 vcc, v4, v2
	v_or_b32_e32 v0, 1, v4
	s_and_b64 s[42:43], s[4:5], vcc
	v_cmp_eq_u32_e32 vcc, v0, v2
	v_or_b32_e32 v0, 2, v4
	s_and_b64 s[44:45], s[4:5], vcc
	v_cmp_eq_u32_e32 vcc, v0, v2
	v_or_b32_e32 v0, 3, v4
	s_and_b64 s[46:47], s[4:5], vcc
	v_cmp_eq_u32_e32 vcc, v0, v2
	v_or_b32_e32 v0, 4, v4
	s_load_dwordx4 s[16:19], s[22:23], 0x68
	s_load_dwordx2 s[36:37], s[22:23], 0x78
	s_and_b64 s[48:49], s[4:5], vcc
	v_cmp_eq_u32_e32 vcc, v0, v2
	v_or_b32_e32 v0, 5, v4
	s_and_b64 s[50:51], s[4:5], vcc
	v_cmp_eq_u32_e32 vcc, v0, v2
	v_or_b32_e32 v0, 6, v4
	s_and_b64 s[52:53], s[4:5], vcc
	v_cmp_eq_u32_e32 vcc, v0, v2
	v_or_b32_e32 v0, 7, v4
	v_lshlrev_b32_e32 v64, 5, v208
	v_lshl_add_u32 v68, v4, 3, 0
	s_and_b64 s[54:55], s[4:5], vcc
	v_cmp_eq_u32_e32 vcc, v0, v2
	v_lshlrev_b32_e32 v0, 5, v210
	v_add_u32_e32 v71, 0, v3
	v_lshl_add_u32 v1, v2, 9, 0
	s_add_i32 s88, 0, 0x22048
	s_mov_b32 s58, 0x652b82fe
	s_mov_b32 s60, 0xfefa39ef
	s_mov_b32 s62, 0x3b39803f
	s_mov_b32 s64, 0x6a5dcb37
	s_mov_b32 s66, 0x6dc9c883
	s_mov_b32 s68, 0x54442d18
	s_mov_b32 s70, 0x33145c07
	s_mov_b32 s72, 0x13a86d09
	s_mov_b32 s74, 0xa8c07c9d
	s_mov_b32 s76, 0
	s_mov_b32 s78, 0
	v_cmp_gt_u32_e64 s[6:7], 64, v208
	v_lshrrev_b32_e32 v66, 1, v208
	v_and_b32_e32 v70, 0x3c0, v64
	s_and_b64 s[56:57], s[4:5], vcc
	v_add_u32_e32 v72, 0xfffffe00, v208
	v_add_u32_e32 v73, 0x2200, v71
	v_lshrrev_b32_e32 v74, 2, v208
	v_add_u32_e32 v75, 0x4200, v71
	v_add_u32_e32 v76, 0x4200, v1
	v_add_u32_e32 v77, 0x2200, v68
	s_mov_b32 s59, 0x3ff71547
	s_mov_b32 s61, 0xbfe62e42
	s_mov_b32 s63, 0xbc7abc9e
	s_mov_b32 s65, 0x3e5ade15
	s_mov_b32 s67, 0x3fe45f30
	s_mov_b32 s69, 0xbff921fb
	s_mov_b32 s71, 0xbc91a626
	s_mov_b32 s73, 0x3de61246
	s_mov_b32 s75, 0xbda93974
	s_mov_b32 s77, 0x40900000
	s_mov_b32 s79, 0xc090cc00
	v_add_u32_e32 v78, 0, v0
	s_movk_i32 s92, 0x80
	s_movk_i32 s94, 0x23f
	s_mov_b64 s[80:81], 0x800
	s_mov_b32 s95, 0xaaaaaaab
	s_movk_i32 s96, 0x300
	v_mov_b32_e32 v79, s88
	v_mov_b32_e32 v12, 0xfca7ab0c
	v_mov_b32_e32 v13, 0x3e928af3
	v_mov_b32_e32 v14, 0x623fde64
	v_mov_b32_e32 v15, 0x3ec71dee
	v_mov_b32_e32 v16, 0x7c89e6b0
	v_mov_b32_e32 v17, 0x3efa0199
	v_mov_b32_e32 v18, 0x14761f6e
	v_mov_b32_e32 v19, 0x3f2a01a0
	v_mov_b32_e32 v20, 0x1852b7b0
	v_mov_b32_e32 v21, 0x3f56c16c
	v_mov_b32_e32 v22, 0x11122322
	v_mov_b32_e32 v23, 0x3f811111
	v_mov_b32_e32 v24, 0x555502a1
	v_mov_b32_e32 v25, 0x3fa55555
	v_mov_b32_e32 v26, 0x55555511
	v_mov_b32_e32 v27, 0x3fc55555
	v_mov_b32_e32 v28, 11
	v_mov_b32_e32 v29, 0x3fe00000
	v_mov_b32_e32 v80, 0x7ff00000
	v_mov_b32_e32 v30, 0x67f544e4
	v_mov_b32_e32 v31, 0xbe5ae645
	v_mov_b32_e32 v32, 0xa556c734
	v_mov_b32_e32 v33, 0x3ec71de3
	v_mov_b32_e32 v34, 0x1a01a01a
	v_mov_b32_e32 v35, 0xbf2a01a0
	v_mov_b32_e32 v36, 0x11111111
	v_mov_b32_e32 v38, 0x55555555
	v_mov_b32_e32 v39, 0xbfc55555
	v_mov_b32_e32 v40, 0xeff8d898
	v_mov_b32_e32 v41, 0x3e21eed8
	v_mov_b32_e32 v42, 0xb7789f5c
	v_mov_b32_e32 v43, 0xbe927e4f
	v_mov_b32_e32 v45, 0x3efa01a0
	v_mov_b32_e32 v46, 0x16c16c17
	v_mov_b32_e32 v47, 0xbf56c16c
	v_mov_b32_e32 v81, 0x3ff00000
	s_branch .Lssa_450
